# v26 + one static s_setprio 1 for waves 4-7 during phase 2 (reset at phase end)
# baseline (speedup 1.0000x reference)
.LBB0_405:
	s_or_b64 exec, exec, s[0:1]
	s_abs_i32 s0, s3
	v_cvt_f32_u32_e32 v0, s0
	s_sub_i32 s5, 0, s0
	s_add_i32 s1, s3, 0xd7f
	s_xor_b32 s4, s1, s3
	v_rcp_iflag_f32_e32 v0, v0
	s_abs_i32 s1, s1
	s_ashr_i32 s4, s4, 31
	s_mov_b32 s97, 0
	v_mul_f32_e32 v0, 0x4f7ffffe, v0
	v_cvt_u32_f32_e32 v0, v0
	s_waitcnt lgkmcnt(0)
	s_barrier
	v_readfirstlane_b32 s6, v0
	s_mul_i32 s5, s5, s6
	s_mul_hi_u32 s5, s6, s5
	s_add_i32 s6, s6, s5
	s_mul_hi_u32 s5, s1, s6
	s_mul_i32 s6, s5, s0
	s_sub_i32 s1, s1, s6
	s_add_i32 s7, s5, 1
	s_sub_i32 s6, s1, s0
	s_cmp_ge_u32 s1, s0
	s_cselect_b32 s5, s7, s5
	s_cselect_b32 s1, s6, s1
	s_add_i32 s6, s5, 1
	s_cmp_ge_u32 s1, s0
	s_cselect_b32 s0, s6, s5
	s_xor_b32 s0, s0, s4
	s_sub_i32 s35, s0, s4
	v_cvt_f32_u32_e32 v0, s35
	s_lshr_b32 s0, s2, 3
	v_writelane_b32 v255, s0, 0
	s_cmp_lt_i32 s35, 1
	v_rcp_iflag_f32_e32 v0, v0
	s_nop 0
	v_mul_f32_e32 v0, 0x4f7ffffe, v0
	v_cvt_u32_f32_e32 v0, v0
	s_nop 0
	v_readfirstlane_b32 s0, v0
	s_cbranch_scc1 .LBB0_1041
	s_sub_i32 s1, 0, s35
	s_mul_i32 s1, s1, s0
	s_mul_hi_u32 s1, s0, s1
	s_add_i32 s0, s0, s1
	v_readlane_b32 s1, v255, 0
	s_mul_hi_u32 s0, s1, s0
	s_mul_i32 s0, s0, s35
	s_sub_i32 s0, s1, s0
	s_sub_i32 s1, s0, s35
	s_cmp_ge_u32 s0, s35
	s_cselect_b32 s0, s1, s0
	s_sub_i32 s1, s0, s35
	s_cmp_ge_u32 s0, s35
	s_cselect_b32 s46, s1, s0
	s_mov_b32 s27, 0x800000
	s_movk_i32 s48, 0x80
	v_mov_b32_e32 v137, 0
	s_movk_i32 s53, 0x300
	s_mov_b32 s24, 0x3f317217
	s_mov_b32 s25, 0x7f800000
	s_movk_i32 s49, 0xbf
	s_mov_b32 s26, 0x8f8d000
	s_mov_b32 s50, 0xf149f2ca
	s_movk_i32 s51, 0x47
	s_movk_i32 s52, 0xa0
	s_movk_i32 s47, 0x90
	s_mov_b32 s54, 0xff61b1e6
	v_mov_b32_e32 v195, 16
	v_mov_b32_e32 v211, 0x180
	v_mbcnt_hi_u32_b32 v193, -1, v193
	v_mov_b32_e32 v213, 0x41b17218
	v_mov_b32_e32 v215, 0xf149f2ca
	s_mov_b32 s55, 0
	v_readfirstlane_b32 s98, v192
	s_lshr_b32 s98, s98, 6
	s_cmp_ge_u32 s98, 4
	s_cbranch_scc0 .Lp2prio_done
	s_setprio 1
.Lp2prio_done:
	s_branch .LBB0_409
.LBB0_407:
	s_or_b64 exec, exec, s[6:7]

.LBB0_1041:
	s_setprio 0
	s_waitcnt vmcnt(0)
	s_waitcnt lgkmcnt(0)
	s_barrier
	s_mov_b64 s[0:1], exec
	v_readlane_b32 s4, v255, 10
	v_readlane_b32 s5, v255, 11
	v_readlane_b32 s54, v255, 48
	s_and_b64 s[4:5], s[0:1], s[4:5]
	v_readlane_b32 s55, v255, 49
	s_mov_b64 exec, s[4:5]
	s_cbranch_execz .LBB0_1093
	v_mov_b32_e32 v0, 0
	s_waitcnt vmcnt(0) expcnt(0) lgkmcnt(0)
	ds_read_b32 v2, v0
	ds_read_b32 v1, v0 offset:4
	s_waitcnt lgkmcnt(1)
	v_cmp_ne_u32_e32 vcc, 0, v2
	s_cbranch_vccnz .LBB0_1057
	v_readlane_b32 s4, v255, 8
	v_readlane_b32 s5, v255, 9
	s_load_dwordx2 s[8:9], s[4:5], 0x4
	s_add_u32 s4, s38, 0xc7b3c00
	s_addc_u32 s5, s39, 0
	s_add_u32 s6, s38, 0xc7b3e00
	s_addc_u32 s7, s39, 0
	s_waitcnt lgkmcnt(0)
	s_mul_i32 s35, s8, s3
	s_add_u32 s8, s38, 0xc7b3f00
	s_mul_i32 s35, s35, s9
	s_addc_u32 s9, s39, 0
	s_add_u32 s10, s38, 0xc7b4000
	s_addc_u32 s11, s39, 0
	s_add_u32 s12, s38, 0xc7b4100
	s_addc_u32 s13, s39, 0
	s_add_u32 s14, s38, 0xc7b4200
	s_addc_u32 s15, s39, 0
	s_add_u32 s16, s38, 0xc7b4300
	s_addc_u32 s17, s39, 0
	s_add_u32 s18, s38, 0xc7b4400
	s_addc_u32 s19, s39, 0
	s_add_u32 s20, s38, 0xc7b4500
	s_addc_u32 s21, s39, 0
	s_add_u32 s22, s38, 0xc7b4600
	s_addc_u32 s23, s39, 0
	s_add_u32 s24, s38, 0xc7b4700
	s_addc_u32 s25, s39, 0
	s_add_u32 s26, s38, 0xc7b4800
	s_addc_u32 s27, s39, 0
	s_add_u32 s28, s38, 0xc7b4900
	s_addc_u32 s29, s39, 0
	s_add_u32 s30, s38, 0xc7b4a00
	s_addc_u32 s31, s39, 0
	s_add_u32 s40, s38, 0xc7b4b00
	s_addc_u32 s41, s39, 0
	s_add_u32 s42, s38, 0xc7b4c00
	s_addc_u32 s43, s39, 0
	s_add_u32 s44, s38, 0xc7b4d00
	s_addc_u32 s45, s39, 0
	s_mov_b32 s52, 1
	s_branch .LBB0_1045
